# mode-2 (residual f32) GEMM epilogue restructured like mode 3: next group's loads before current stores, vmcnt(4) waits
# baseline (speedup 1.0000x reference)
.LBB0_116:
	v_lshl_add_u32 v142, s89, 8, v144
	v_lshl_or_b32 v140, s88, 8, v146
	v_ashrrev_i32_e32 v143, 31, v142
	v_ashrrev_i32_e32 v141, 31, v140
	v_lshlrev_b64 v[138:139], 10, v[142:143]
	v_lshl_add_u64 v[138:139], v[138:139], 0, v[140:141]
	v_lshlrev_b64 v[138:139], 2, v[138:139]
	v_lshl_add_u64 v[160:161], s[44:45], 0, v[138:139]
	global_load_dwordx4 v[148:151], v[160:161], off offset:16
	global_load_dwordx4 v[152:155], v[160:161], off
	global_load_dwordx4 v[156:159], v[160:161], off offset:528
	s_nop 0
	global_load_dwordx4 v[160:163], v[160:161], off offset:512
	s_mov_b64 s[12:13], 0x80000
	s_mov_b64 s[28:29], -1
	s_and_b64 vcc, exec, s[40:41]
	s_waitcnt vmcnt(0)
	v_pk_fma_f32 v[124:125], v[152:153], s[22:23], v[124:125] op_sel_hi:[1,0,1]
	v_pk_fma_f32 v[126:127], v[154:155], s[22:23], v[126:127] op_sel_hi:[1,0,1]
	v_pk_fma_f32 v[120:121], v[148:149], s[22:23], v[120:121] op_sel_hi:[1,0,1]
	v_pk_fma_f32 v[122:123], v[150:151], s[22:23], v[122:123] op_sel_hi:[1,0,1]
	v_pk_fma_f32 v[116:117], v[160:161], s[22:23], v[116:117] op_sel_hi:[1,0,1]
	v_pk_fma_f32 v[118:119], v[162:163], s[22:23], v[118:119] op_sel_hi:[1,0,1]
	v_pk_fma_f32 v[112:113], v[156:157], s[22:23], v[112:113] op_sel_hi:[1,0,1]
	v_pk_fma_f32 v[114:115], v[158:159], s[22:23], v[114:115] op_sel_hi:[1,0,1]
	v_lshl_add_u64 v[248:249], s[46:47], 0, v[138:139]
	s_mov_b64 s[12:13], 0x10000
	v_lshl_add_u64 v[246:247], v[138:139], 0, s[12:13]
	v_lshl_add_u64 v[208:209], s[44:45], 0, v[246:247]
	global_load_dwordx4 v[148:151], v[208:209], off offset:16
	global_load_dwordx4 v[152:155], v[208:209], off
	global_load_dwordx4 v[156:159], v[208:209], off offset:528
	global_load_dwordx4 v[160:163], v[208:209], off offset:512
	global_store_dwordx4 v[248:249], v[124:127], off
	global_store_dwordx4 v[248:249], v[120:123], off offset:16
	global_store_dwordx4 v[248:249], v[116:119], off offset:512
	global_store_dwordx4 v[248:249], v[112:115], off offset:528
	s_waitcnt vmcnt(4)
	v_pk_fma_f32 v[108:109], v[152:153], s[22:23], v[108:109] op_sel_hi:[1,0,1]
	v_pk_fma_f32 v[110:111], v[154:155], s[22:23], v[110:111] op_sel_hi:[1,0,1]
	v_pk_fma_f32 v[104:105], v[148:149], s[22:23], v[104:105] op_sel_hi:[1,0,1]
	v_pk_fma_f32 v[106:107], v[150:151], s[22:23], v[106:107] op_sel_hi:[1,0,1]
	v_pk_fma_f32 v[100:101], v[160:161], s[22:23], v[100:101] op_sel_hi:[1,0,1]
	v_pk_fma_f32 v[102:103], v[162:163], s[22:23], v[102:103] op_sel_hi:[1,0,1]
	v_pk_fma_f32 v[96:97], v[156:157], s[22:23], v[96:97] op_sel_hi:[1,0,1]
	v_pk_fma_f32 v[98:99], v[158:159], s[22:23], v[98:99] op_sel_hi:[1,0,1]
	v_lshl_add_u64 v[248:249], s[46:47], 0, v[246:247]
	s_mov_b64 s[12:13], 0x20000
	v_lshl_add_u64 v[246:247], v[138:139], 0, s[12:13]
	v_lshl_add_u64 v[208:209], s[44:45], 0, v[246:247]
	global_load_dwordx4 v[148:151], v[208:209], off offset:16
	global_load_dwordx4 v[152:155], v[208:209], off
	global_load_dwordx4 v[156:159], v[208:209], off offset:528
	global_load_dwordx4 v[160:163], v[208:209], off offset:512
	global_store_dwordx4 v[248:249], v[108:111], off
	global_store_dwordx4 v[248:249], v[104:107], off offset:16
	global_store_dwordx4 v[248:249], v[100:103], off offset:512
	global_store_dwordx4 v[248:249], v[96:99], off offset:528
	s_waitcnt vmcnt(4)
	v_pk_fma_f32 v[92:93], v[152:153], s[22:23], v[92:93] op_sel_hi:[1,0,1]
	v_pk_fma_f32 v[94:95], v[154:155], s[22:23], v[94:95] op_sel_hi:[1,0,1]
	v_pk_fma_f32 v[88:89], v[148:149], s[22:23], v[88:89] op_sel_hi:[1,0,1]
	v_pk_fma_f32 v[90:91], v[150:151], s[22:23], v[90:91] op_sel_hi:[1,0,1]
	v_pk_fma_f32 v[84:85], v[160:161], s[22:23], v[84:85] op_sel_hi:[1,0,1]
	v_pk_fma_f32 v[86:87], v[162:163], s[22:23], v[86:87] op_sel_hi:[1,0,1]
	v_pk_fma_f32 v[80:81], v[156:157], s[22:23], v[80:81] op_sel_hi:[1,0,1]
	v_pk_fma_f32 v[82:83], v[158:159], s[22:23], v[82:83] op_sel_hi:[1,0,1]
	v_lshl_add_u64 v[248:249], s[46:47], 0, v[246:247]
	s_mov_b64 s[12:13], 0x30000
	v_lshl_add_u64 v[246:247], v[138:139], 0, s[12:13]
	v_lshl_add_u64 v[208:209], s[44:45], 0, v[246:247]
	global_load_dwordx4 v[148:151], v[208:209], off offset:16
	global_load_dwordx4 v[152:155], v[208:209], off
	global_load_dwordx4 v[156:159], v[208:209], off offset:528
	global_load_dwordx4 v[160:163], v[208:209], off offset:512
	global_store_dwordx4 v[248:249], v[92:95], off
	global_store_dwordx4 v[248:249], v[88:91], off offset:16
	global_store_dwordx4 v[248:249], v[84:87], off offset:512
	global_store_dwordx4 v[248:249], v[80:83], off offset:528
	s_waitcnt vmcnt(4)
	v_pk_fma_f32 v[76:77], v[152:153], s[22:23], v[76:77] op_sel_hi:[1,0,1]
	v_pk_fma_f32 v[78:79], v[154:155], s[22:23], v[78:79] op_sel_hi:[1,0,1]
	v_pk_fma_f32 v[72:73], v[148:149], s[22:23], v[72:73] op_sel_hi:[1,0,1]
	v_pk_fma_f32 v[74:75], v[150:151], s[22:23], v[74:75] op_sel_hi:[1,0,1]
	v_pk_fma_f32 v[68:69], v[160:161], s[22:23], v[68:69] op_sel_hi:[1,0,1]
	v_pk_fma_f32 v[70:71], v[162:163], s[22:23], v[70:71] op_sel_hi:[1,0,1]
	v_pk_fma_f32 v[64:65], v[156:157], s[22:23], v[64:65] op_sel_hi:[1,0,1]
	v_pk_fma_f32 v[66:67], v[158:159], s[22:23], v[66:67] op_sel_hi:[1,0,1]
	v_lshl_add_u64 v[248:249], s[46:47], 0, v[246:247]
	s_mov_b64 s[12:13], 0x80000
	v_lshl_add_u64 v[246:247], v[138:139], 0, s[12:13]
	v_lshl_add_u64 v[208:209], s[44:45], 0, v[246:247]
	global_load_dwordx4 v[148:151], v[208:209], off offset:16
	global_load_dwordx4 v[152:155], v[208:209], off
	global_load_dwordx4 v[156:159], v[208:209], off offset:528
	global_load_dwordx4 v[160:163], v[208:209], off offset:512
	global_store_dwordx4 v[248:249], v[76:79], off
	global_store_dwordx4 v[248:249], v[72:75], off offset:16
	global_store_dwordx4 v[248:249], v[68:71], off offset:512
	global_store_dwordx4 v[248:249], v[64:67], off offset:528
	s_waitcnt vmcnt(4)
	v_pk_fma_f32 v[60:61], v[152:153], s[22:23], v[60:61] op_sel_hi:[1,0,1]
	v_pk_fma_f32 v[62:63], v[154:155], s[22:23], v[62:63] op_sel_hi:[1,0,1]
	v_pk_fma_f32 v[56:57], v[148:149], s[22:23], v[56:57] op_sel_hi:[1,0,1]
	v_pk_fma_f32 v[58:59], v[150:151], s[22:23], v[58:59] op_sel_hi:[1,0,1]
	v_pk_fma_f32 v[52:53], v[160:161], s[22:23], v[52:53] op_sel_hi:[1,0,1]
	v_pk_fma_f32 v[54:55], v[162:163], s[22:23], v[54:55] op_sel_hi:[1,0,1]
	v_pk_fma_f32 v[48:49], v[156:157], s[22:23], v[48:49] op_sel_hi:[1,0,1]
	v_pk_fma_f32 v[50:51], v[158:159], s[22:23], v[50:51] op_sel_hi:[1,0,1]
	v_lshl_add_u64 v[248:249], s[46:47], 0, v[246:247]
	s_mov_b64 s[12:13], 0x90000
	v_lshl_add_u64 v[246:247], v[138:139], 0, s[12:13]
	v_lshl_add_u64 v[208:209], s[44:45], 0, v[246:247]
	global_load_dwordx4 v[148:151], v[208:209], off offset:16
	global_load_dwordx4 v[152:155], v[208:209], off
	global_load_dwordx4 v[156:159], v[208:209], off offset:528
	global_load_dwordx4 v[160:163], v[208:209], off offset:512
	global_store_dwordx4 v[248:249], v[60:63], off
	global_store_dwordx4 v[248:249], v[56:59], off offset:16
	global_store_dwordx4 v[248:249], v[52:55], off offset:512
	global_store_dwordx4 v[248:249], v[48:51], off offset:528
	s_waitcnt vmcnt(4)
	v_pk_fma_f32 v[44:45], v[152:153], s[22:23], v[44:45] op_sel_hi:[1,0,1]
	v_pk_fma_f32 v[46:47], v[154:155], s[22:23], v[46:47] op_sel_hi:[1,0,1]
	v_pk_fma_f32 v[40:41], v[148:149], s[22:23], v[40:41] op_sel_hi:[1,0,1]
	v_pk_fma_f32 v[42:43], v[150:151], s[22:23], v[42:43] op_sel_hi:[1,0,1]
	v_pk_fma_f32 v[36:37], v[160:161], s[22:23], v[36:37] op_sel_hi:[1,0,1]
	v_pk_fma_f32 v[38:39], v[162:163], s[22:23], v[38:39] op_sel_hi:[1,0,1]
	v_pk_fma_f32 v[32:33], v[156:157], s[22:23], v[32:33] op_sel_hi:[1,0,1]
	v_pk_fma_f32 v[34:35], v[158:159], s[22:23], v[34:35] op_sel_hi:[1,0,1]
	v_lshl_add_u64 v[248:249], s[46:47], 0, v[246:247]
	s_mov_b64 s[12:13], 0xa0000
	v_lshl_add_u64 v[246:247], v[138:139], 0, s[12:13]
	v_lshl_add_u64 v[208:209], s[44:45], 0, v[246:247]
	global_load_dwordx4 v[148:151], v[208:209], off offset:16
	global_load_dwordx4 v[152:155], v[208:209], off
	global_load_dwordx4 v[156:159], v[208:209], off offset:528
	global_load_dwordx4 v[160:163], v[208:209], off offset:512
	global_store_dwordx4 v[248:249], v[44:47], off
	global_store_dwordx4 v[248:249], v[40:43], off offset:16
	global_store_dwordx4 v[248:249], v[36:39], off offset:512
	global_store_dwordx4 v[248:249], v[32:35], off offset:528
	s_waitcnt vmcnt(4)
	v_pk_fma_f32 v[28:29], v[152:153], s[22:23], v[28:29] op_sel_hi:[1,0,1]
	v_pk_fma_f32 v[30:31], v[154:155], s[22:23], v[30:31] op_sel_hi:[1,0,1]
	v_pk_fma_f32 v[24:25], v[148:149], s[22:23], v[24:25] op_sel_hi:[1,0,1]
	v_pk_fma_f32 v[26:27], v[150:151], s[22:23], v[26:27] op_sel_hi:[1,0,1]
	v_pk_fma_f32 v[20:21], v[160:161], s[22:23], v[20:21] op_sel_hi:[1,0,1]
	v_pk_fma_f32 v[22:23], v[162:163], s[22:23], v[22:23] op_sel_hi:[1,0,1]
	v_pk_fma_f32 v[16:17], v[156:157], s[22:23], v[16:17] op_sel_hi:[1,0,1]
	v_pk_fma_f32 v[18:19], v[158:159], s[22:23], v[18:19] op_sel_hi:[1,0,1]
	v_lshl_add_u64 v[248:249], s[46:47], 0, v[246:247]
	s_mov_b64 s[12:13], 0xb0000
	v_lshl_add_u64 v[246:247], v[138:139], 0, s[12:13]
	v_lshl_add_u64 v[208:209], s[44:45], 0, v[246:247]
	global_load_dwordx4 v[148:151], v[208:209], off offset:16
	global_load_dwordx4 v[152:155], v[208:209], off
	global_load_dwordx4 v[156:159], v[208:209], off offset:528
	global_load_dwordx4 v[160:163], v[208:209], off offset:512
	global_store_dwordx4 v[248:249], v[28:31], off
	global_store_dwordx4 v[248:249], v[24:27], off offset:16
	global_store_dwordx4 v[248:249], v[20:23], off offset:512
	global_store_dwordx4 v[248:249], v[16:19], off offset:528
	s_waitcnt vmcnt(4)
	v_pk_fma_f32 v[12:13], v[152:153], s[22:23], v[12:13] op_sel_hi:[1,0,1]
	v_pk_fma_f32 v[14:15], v[154:155], s[22:23], v[14:15] op_sel_hi:[1,0,1]
	v_pk_fma_f32 v[8:9], v[148:149], s[22:23], v[8:9] op_sel_hi:[1,0,1]
	v_pk_fma_f32 v[10:11], v[150:151], s[22:23], v[10:11] op_sel_hi:[1,0,1]
	v_pk_fma_f32 v[4:5], v[160:161], s[22:23], v[4:5] op_sel_hi:[1,0,1]
	v_pk_fma_f32 v[6:7], v[162:163], s[22:23], v[6:7] op_sel_hi:[1,0,1]
	v_pk_fma_f32 v[0:1], v[156:157], s[22:23], v[0:1] op_sel_hi:[1,0,1]
	v_pk_fma_f32 v[2:3], v[158:159], s[22:23], v[2:3] op_sel_hi:[1,0,1]
	v_lshl_add_u64 v[248:249], s[46:47], 0, v[246:247]
	global_store_dwordx4 v[248:249], v[12:15], off
	global_store_dwordx4 v[248:249], v[8:11], off offset:16
	global_store_dwordx4 v[248:249], v[4:7], off offset:512
	global_store_dwordx4 v[248:249], v[0:3], off offset:528
	s_cbranch_vccnz .LBB0_106
	s_andn2_b64 vcc, exec, s[50:51]
	s_cbranch_vccnz .LBB0_105
	s_barrier
	s_branch .LBB0_105
